# P1 projection stores: sc1 plus nt streaming hint (P is written once and read in the next phase)
# speedup vs baseline: 1.0124x; 1.0124x over previous
; __device__ __forceinline__ unsigned cvt_pk_bf16(float lo, float hi) { unsigned r; asm volatile("v_cvt_pk_bf16_f32 %0, %1, %2" : "=v"(r) : "v"(lo), "v"(hi)); return r; }
;     __device__ __forceinline__ void operator()(const f32x4 (&acc)[2][2][4][2], const Unit& u, int wr, int wc, int fr, int fq) const {
;         const int row0 = u.pm * BM + wr * 64 + fr, col0 = u.pn * BM + wc * 32 + 8 * fq, pn = u.pn;
;         const float sc = (pn < 6 || (pn >= 20 && pn < 22) || (pn >= 25 && pn < 27)) ? 0.125f * 1.4426950408889634f : 1.0f;
;         float rsv[2][4];
; #pragma unroll
;         for (int ai = 0; ai < 2; ++ai)
; #pragma unroll
;             for (int m = 0; m < 4; ++m) rsv[ai][m] = rowss[row0 + ai * HALF + m * 16];
; #pragma unroll
;         for (int ai = 0; ai < 2; ++ai)
; #pragma unroll
;             for (int m = 0; m < 4; ++m) { const int row = row0 + ai * HALF + m * 16; const float rs = rsqrtf(rsv[ai][m] * (1.0f / 1024.0f) + 1e-6f) * sc;
; #pragma unroll
;                 for (int bj = 0; bj < 2; ++bj) { const f32x4 v0 = acc[ai][bj][m][0] * rs, v1 = acc[ai][bj][m][1] * rs;
;                     u32x4 w; w.x = cvt_pk_bf16(v0[0], v0[1]); w.y = cvt_pk_bf16(v0[2], v0[3]); w.z = cvt_pk_bf16(v1[0], v1[1]); w.w = cvt_pk_bf16(v1[2], v1[3]);
;                     *(u32x4*)(O + PB(col0 + bj * HALF) + (size_t)row * 64) = w; } }
.LBB0_138:
	v_lshl_add_u32 v140, s57, 8, v154
	v_ashrrev_i32_e32 v141, 31, v140
	s_cmp_lt_i32 s46, 6
	s_cselect_b64 s[12:13], -1, 0
	s_and_b32 s21, s46, 0x7ffffffe
	s_cmp_eq_u32 s21, 20
	s_cselect_b64 s[28:29], -1, 0
	s_or_b64 s[12:13], s[12:13], s[28:29]
	s_sub_i32 s21, s46, 25
	s_cmp_lt_u32 s21, 2
	s_cselect_b64 s[28:29], -1, 0
	s_or_b64 vcc, s[12:13], s[28:29]
	v_cndmask_b32_e32 v157, 1.0, v237, vcc
	v_lshlrev_b64 v[166:167], 7, v[140:141]
	s_mov_b64 s[12:13], 0x4000
	v_lshl_add_u64 v[146:147], v[166:167], 0, s[12:13]
	s_mov_b64 s[12:13], 0x4800
	v_lshl_add_u64 v[144:145], v[166:167], 0, s[12:13]
	s_mov_b64 s[12:13], 0x5000
	v_lshl_add_u64 v[142:143], v[166:167], 0, s[12:13]
	s_mov_b64 s[12:13], 0x5800
	v_or_b32_e32 v152, 16, v140
	v_or_b32_e32 v150, 32, v140
	v_or_b32_e32 v148, 48, v140
	v_lshl_add_u64 v[140:141], v[166:167], 0, s[12:13]
	s_lshl_b32 s12, s46, 8
	s_or_b32 s12, s12, s49
	s_ashr_i32 s12, s12, 6
	s_ashr_i32 s13, s12, 31
	s_lshl_b64 s[28:29], s[12:13], 21
	s_or_b32 s12, s12, 2
	s_ashr_i32 s13, s12, 31
	s_lshl_b64 s[12:13], s[12:13], 21
	v_ashrrev_i32_e32 v153, 31, v152
	v_ashrrev_i32_e32 v151, 31, v150
	v_ashrrev_i32_e32 v149, 31, v148
	s_waitcnt vmcnt(8)
	v_fmamk_f32 v164, v241, 0x3a800000, v230
	v_cmp_gt_f32_e32 vcc, s37, v164
	v_mul_f32_e32 v165, 0x4b800000, v164
	s_nop 0
	v_cndmask_b32_e32 v164, v164, v165, vcc
	v_rsq_f32_e32 v164, v164
	s_nop 0
	v_mul_f32_e32 v165, 0x45800000, v164
	v_cndmask_b32_e32 v164, v164, v165, vcc
	v_mul_f32_e32 v164, v157, v164
	v_pk_mul_f32 v[124:125], v[124:125], v[164:165] op_sel_hi:[1,0]
	v_pk_mul_f32 v[120:121], v[120:121], v[164:165] op_sel_hi:[1,0]
	v_pk_mul_f32 v[126:127], v[126:127], v[164:165] op_sel_hi:[1,0]
	v_pk_mul_f32 v[168:169], v[122:123], v[164:165] op_sel_hi:[1,0]
	v_cvt_pk_bf16_f32 v122, v124, v125
	v_cvt_pk_bf16_f32 v123, v126, v127
	v_cvt_pk_bf16_f32 v124, v120, v121
	v_lshl_add_u64 v[120:121], v[134:135], 0, s[28:29]
	v_lshl_add_u64 v[126:127], v[120:121], 0, v[166:167]
	v_pk_mul_f32 v[116:117], v[116:117], v[164:165] op_sel_hi:[1,0]
	v_pk_mul_f32 v[112:113], v[112:113], v[164:165] op_sel_hi:[1,0]
	v_cvt_pk_bf16_f32 v125, v168, v169
	global_store_dwordx4 v[126:127], v[122:125], off sc1 nt
	v_pk_mul_f32 v[118:119], v[118:119], v[164:165] op_sel_hi:[1,0]
	s_nop 0
	v_pk_mul_f32 v[122:123], v[114:115], v[164:165] op_sel_hi:[1,0]
	v_cvt_pk_bf16_f32 v114, v116, v117
	v_cvt_pk_bf16_f32 v115, v118, v119
	v_cvt_pk_bf16_f32 v116, v112, v113
	v_lshl_add_u64 v[112:113], v[134:135], 0, s[12:13]
	v_lshl_add_u64 v[118:119], v[112:113], 0, v[166:167]
	v_cvt_pk_bf16_f32 v117, v122, v123
	global_store_dwordx4 v[118:119], v[114:117], off sc1 nt
	s_mov_b64 s[12:13], -1
	s_nop 0
	v_fmamk_f32 v114, v242, 0x3a800000, v230
	v_cmp_gt_f32_e32 vcc, s37, v114
	v_mul_f32_e32 v115, 0x4b800000, v114
	v_lshlrev_b64 v[116:117], 7, v[152:153]
	v_cndmask_b32_e32 v114, v114, v115, vcc
	v_rsq_f32_e32 v114, v114
	s_nop 0
	v_mul_f32_e32 v115, 0x45800000, v114
	v_cndmask_b32_e32 v114, v114, v115, vcc
	v_mul_f32_e32 v114, v157, v114
	v_pk_mul_f32 v[108:109], v[108:109], v[114:115] op_sel_hi:[1,0]
	v_pk_mul_f32 v[110:111], v[110:111], v[114:115] op_sel_hi:[1,0]
	v_pk_mul_f32 v[118:119], v[106:107], v[114:115] op_sel_hi:[1,0]
	v_pk_mul_f32 v[106:107], v[104:105], v[114:115] op_sel_hi:[1,0]
	v_cvt_pk_bf16_f32 v104, v108, v109
	v_cvt_pk_bf16_f32 v105, v110, v111
	v_lshl_add_u64 v[108:109], v[120:121], 0, v[116:117]
	v_pk_mul_f32 v[100:101], v[100:101], v[114:115] op_sel_hi:[1,0]
	v_cvt_pk_bf16_f32 v106, v106, v107
	v_cvt_pk_bf16_f32 v107, v118, v119
	global_store_dwordx4 v[108:109], v[104:107], off sc1 nt
	v_pk_mul_f32 v[102:103], v[102:103], v[114:115] op_sel_hi:[1,0]
	s_nop 0
	v_pk_mul_f32 v[104:105], v[98:99], v[114:115] op_sel_hi:[1,0]
	v_pk_mul_f32 v[98:99], v[96:97], v[114:115] op_sel_hi:[1,0]
	v_cvt_pk_bf16_f32 v96, v100, v101
	v_lshl_add_u64 v[100:101], v[112:113], 0, v[116:117]
	v_cvt_pk_bf16_f32 v97, v102, v103
	v_cvt_pk_bf16_f32 v98, v98, v99
	v_cvt_pk_bf16_f32 v99, v104, v105
	global_store_dwordx4 v[100:101], v[96:99], off sc1 nt
	s_nop 1
	v_fmamk_f32 v96, v243, 0x3a800000, v230
	v_cmp_gt_f32_e32 vcc, s37, v96
	v_mul_f32_e32 v97, 0x4b800000, v96
	v_lshlrev_b64 v[98:99], 7, v[150:151]
	v_cndmask_b32_e32 v96, v96, v97, vcc
	v_rsq_f32_e32 v96, v96
	s_nop 0
	v_mul_f32_e32 v97, 0x45800000, v96
	v_cndmask_b32_e32 v96, v96, v97, vcc
	v_mul_f32_e32 v96, v157, v96
	v_pk_mul_f32 v[92:93], v[92:93], v[96:97] op_sel_hi:[1,0]
	v_pk_mul_f32 v[94:95], v[94:95], v[96:97] op_sel_hi:[1,0]
	v_pk_mul_f32 v[100:101], v[90:91], v[96:97] op_sel_hi:[1,0]
	v_pk_mul_f32 v[90:91], v[88:89], v[96:97] op_sel_hi:[1,0]
	v_cvt_pk_bf16_f32 v88, v92, v93
	v_cvt_pk_bf16_f32 v89, v94, v95
	v_lshl_add_u64 v[92:93], v[120:121], 0, v[98:99]
	v_pk_mul_f32 v[84:85], v[84:85], v[96:97] op_sel_hi:[1,0]
	v_cvt_pk_bf16_f32 v90, v90, v91
	v_cvt_pk_bf16_f32 v91, v100, v101
	global_store_dwordx4 v[92:93], v[88:91], off sc1 nt
	v_pk_mul_f32 v[86:87], v[86:87], v[96:97] op_sel_hi:[1,0]
	s_nop 0
	v_pk_mul_f32 v[88:89], v[82:83], v[96:97] op_sel_hi:[1,0]
	v_pk_mul_f32 v[82:83], v[80:81], v[96:97] op_sel_hi:[1,0]
	v_cvt_pk_bf16_f32 v80, v84, v85
	v_lshl_add_u64 v[84:85], v[112:113], 0, v[98:99]
	v_cvt_pk_bf16_f32 v81, v86, v87
	v_cvt_pk_bf16_f32 v82, v82, v83
	v_cvt_pk_bf16_f32 v83, v88, v89
	global_store_dwordx4 v[84:85], v[80:83], off sc1 nt
	s_nop 1
	v_fmamk_f32 v80, v244, 0x3a800000, v230
	v_cmp_gt_f32_e32 vcc, s37, v80
	v_mul_f32_e32 v81, 0x4b800000, v80
	v_lshlrev_b64 v[82:83], 7, v[148:149]
	v_cndmask_b32_e32 v80, v80, v81, vcc
	v_rsq_f32_e32 v80, v80
	s_nop 0
	v_mul_f32_e32 v81, 0x45800000, v80
	v_cndmask_b32_e32 v80, v80, v81, vcc
; __device__ __forceinline__ unsigned cvt_pk_bf16(float lo, float hi) { unsigned r; asm volatile("v_cvt_pk_bf16_f32 %0, %1, %2" : "=v"(r) : "v"(lo), "v"(hi)); return r; }
; #define PG8_BAR __builtin_amdgcn_s_barrier()
;     __device__ __forceinline__ void operator()(const f32x4 (&acc)[2][2][4][2], const Unit& u, int wr, int wc, int fr, int fq) const {
;     ...
;             for (int m = 0; m < 4; ++m) { const int row = row0 + ai * HALF + m * 16; const float rs = rsqrtf(rsv[ai][m] * (1.0f / 1024.0f) + 1e-6f) * sc;
; #pragma unroll
;                 for (int bj = 0; bj < 2; ++bj) { const f32x4 v0 = acc[ai][bj][m][0] * rs, v1 = acc[ai][bj][m][1] * rs;
;                     u32x4 w; w.x = cvt_pk_bf16(v0[0], v0[1]); w.y = cvt_pk_bf16(v0[2], v0[3]); w.z = cvt_pk_bf16(v1[0], v1[1]); w.w = cvt_pk_bf16(v1[2], v1[3]);
;                     *(u32x4*)(O + PB(col0 + bj * HALF) + (size_t)row * 64) = w; } }
; template <class Epi, class Sched, bool ALIGN_EPI = false, bool SP2 = false>
; __device__ __forceinline__ void gemm_phase(PG8_LAS unsigned char* lds, const Gemm g, const Sched& S, const Epi& E) {
;     ...
;         if (!has_next) break;
; #pragma unroll
;         for (int a = 0; a < 2; ++a)
; #pragma unroll
;             for (int b = 0; b < 2; ++b)
; #pragma unroll
;                 for (int m = 0; m < 4; ++m)
; #pragma unroll
;                     for (int n = 0; n < 2; ++n) acc[a][b][m][n] = (f32x4){0.f, 0.f, 0.f, 0.f};
;         cur = nxt; cA = nA; cB = nB; ++ui;
;         if constexpr (ALIGN_EPI) { if (wr == 1) PG8_BAR; }
	v_mul_f32_e32 v80, v157, v80
	v_pk_mul_f32 v[76:77], v[76:77], v[80:81] op_sel_hi:[1,0]
	v_pk_mul_f32 v[78:79], v[78:79], v[80:81] op_sel_hi:[1,0]
	v_pk_mul_f32 v[84:85], v[74:75], v[80:81] op_sel_hi:[1,0]
	v_pk_mul_f32 v[74:75], v[72:73], v[80:81] op_sel_hi:[1,0]
	v_cvt_pk_bf16_f32 v72, v76, v77
	v_cvt_pk_bf16_f32 v73, v78, v79
	v_lshl_add_u64 v[76:77], v[120:121], 0, v[82:83]
	v_pk_mul_f32 v[68:69], v[68:69], v[80:81] op_sel_hi:[1,0]
	v_cvt_pk_bf16_f32 v74, v74, v75
	v_cvt_pk_bf16_f32 v75, v84, v85
	global_store_dwordx4 v[76:77], v[72:75], off sc1 nt
	v_pk_mul_f32 v[70:71], v[70:71], v[80:81] op_sel_hi:[1,0]
	s_nop 0
	v_pk_mul_f32 v[72:73], v[66:67], v[80:81] op_sel_hi:[1,0]
	v_pk_mul_f32 v[66:67], v[64:65], v[80:81] op_sel_hi:[1,0]
	v_cvt_pk_bf16_f32 v64, v68, v69
	v_lshl_add_u64 v[68:69], v[112:113], 0, v[82:83]
	v_cvt_pk_bf16_f32 v65, v70, v71
	v_cvt_pk_bf16_f32 v66, v66, v67
	v_cvt_pk_bf16_f32 v67, v72, v73
	global_store_dwordx4 v[68:69], v[64:67], off sc1 nt
	s_nop 1
	v_fmamk_f32 v64, v245, 0x3a800000, v230
	v_cmp_gt_f32_e32 vcc, s37, v64
	v_mul_f32_e32 v65, 0x4b800000, v64
	s_nop 0
	v_cndmask_b32_e32 v64, v64, v65, vcc
	v_rsq_f32_e32 v64, v64
	s_nop 0
	v_mul_f32_e32 v65, 0x45800000, v64
	v_cndmask_b32_e32 v64, v64, v65, vcc
	v_mul_f32_e32 v64, v157, v64
	v_pk_mul_f32 v[60:61], v[60:61], v[64:65] op_sel_hi:[1,0]
	v_pk_mul_f32 v[62:63], v[62:63], v[64:65] op_sel_hi:[1,0]
	v_pk_mul_f32 v[66:67], v[58:59], v[64:65] op_sel_hi:[1,0]
	v_pk_mul_f32 v[58:59], v[56:57], v[64:65] op_sel_hi:[1,0]
	v_cvt_pk_bf16_f32 v56, v60, v61
	v_cvt_pk_bf16_f32 v57, v62, v63
	v_lshl_add_u64 v[60:61], v[120:121], 0, v[146:147]
	v_pk_mul_f32 v[52:53], v[52:53], v[64:65] op_sel_hi:[1,0]
	v_cvt_pk_bf16_f32 v58, v58, v59
	v_cvt_pk_bf16_f32 v59, v66, v67
	global_store_dwordx4 v[60:61], v[56:59], off sc1 nt
	v_pk_mul_f32 v[54:55], v[54:55], v[64:65] op_sel_hi:[1,0]
	s_nop 0
	v_pk_mul_f32 v[56:57], v[50:51], v[64:65] op_sel_hi:[1,0]
	v_pk_mul_f32 v[50:51], v[48:49], v[64:65] op_sel_hi:[1,0]
	v_cvt_pk_bf16_f32 v48, v52, v53
	v_lshl_add_u64 v[52:53], v[112:113], 0, v[146:147]
	v_cvt_pk_bf16_f32 v49, v54, v55
	v_cvt_pk_bf16_f32 v50, v50, v51
	v_cvt_pk_bf16_f32 v51, v56, v57
	global_store_dwordx4 v[52:53], v[48:51], off sc1 nt
	s_nop 1
	v_fmamk_f32 v48, v246, 0x3a800000, v230
	v_cmp_gt_f32_e32 vcc, s37, v48
	v_mul_f32_e32 v49, 0x4b800000, v48
	s_nop 0
	v_cndmask_b32_e32 v48, v48, v49, vcc
	v_rsq_f32_e32 v48, v48
	s_nop 0
	v_mul_f32_e32 v49, 0x45800000, v48
	v_cndmask_b32_e32 v48, v48, v49, vcc
	v_mul_f32_e32 v48, v157, v48
	v_pk_mul_f32 v[44:45], v[44:45], v[48:49] op_sel_hi:[1,0]
	v_pk_mul_f32 v[46:47], v[46:47], v[48:49] op_sel_hi:[1,0]
	v_pk_mul_f32 v[50:51], v[42:43], v[48:49] op_sel_hi:[1,0]
	v_pk_mul_f32 v[42:43], v[40:41], v[48:49] op_sel_hi:[1,0]
	v_cvt_pk_bf16_f32 v40, v44, v45
	v_cvt_pk_bf16_f32 v41, v46, v47
	v_lshl_add_u64 v[44:45], v[120:121], 0, v[144:145]
	v_pk_mul_f32 v[36:37], v[36:37], v[48:49] op_sel_hi:[1,0]
	v_cvt_pk_bf16_f32 v42, v42, v43
	v_cvt_pk_bf16_f32 v43, v50, v51
	global_store_dwordx4 v[44:45], v[40:43], off sc1 nt
	v_pk_mul_f32 v[38:39], v[38:39], v[48:49] op_sel_hi:[1,0]
	s_nop 0
	v_pk_mul_f32 v[40:41], v[34:35], v[48:49] op_sel_hi:[1,0]
	v_pk_mul_f32 v[34:35], v[32:33], v[48:49] op_sel_hi:[1,0]
	v_cvt_pk_bf16_f32 v32, v36, v37
	v_lshl_add_u64 v[36:37], v[112:113], 0, v[144:145]
	v_cvt_pk_bf16_f32 v33, v38, v39
	v_cvt_pk_bf16_f32 v34, v34, v35
	v_cvt_pk_bf16_f32 v35, v40, v41
	global_store_dwordx4 v[36:37], v[32:35], off sc1 nt
	s_nop 1
	v_fmamk_f32 v32, v247, 0x3a800000, v230
	v_cmp_gt_f32_e32 vcc, s37, v32
	v_mul_f32_e32 v33, 0x4b800000, v32
	s_nop 0
	v_cndmask_b32_e32 v32, v32, v33, vcc
	v_rsq_f32_e32 v32, v32
	s_nop 0
	v_mul_f32_e32 v33, 0x45800000, v32
	v_cndmask_b32_e32 v32, v32, v33, vcc
	v_mul_f32_e32 v32, v157, v32
	v_pk_mul_f32 v[28:29], v[28:29], v[32:33] op_sel_hi:[1,0]
	v_pk_mul_f32 v[30:31], v[30:31], v[32:33] op_sel_hi:[1,0]
	v_pk_mul_f32 v[34:35], v[26:27], v[32:33] op_sel_hi:[1,0]
	v_pk_mul_f32 v[26:27], v[24:25], v[32:33] op_sel_hi:[1,0]
	v_cvt_pk_bf16_f32 v24, v28, v29
	v_cvt_pk_bf16_f32 v25, v30, v31
	v_lshl_add_u64 v[28:29], v[120:121], 0, v[142:143]
	v_pk_mul_f32 v[20:21], v[20:21], v[32:33] op_sel_hi:[1,0]
	v_cvt_pk_bf16_f32 v26, v26, v27
	v_cvt_pk_bf16_f32 v27, v34, v35
	global_store_dwordx4 v[28:29], v[24:27], off sc1 nt
	v_pk_mul_f32 v[22:23], v[22:23], v[32:33] op_sel_hi:[1,0]
	s_nop 0
	v_pk_mul_f32 v[24:25], v[18:19], v[32:33] op_sel_hi:[1,0]
	v_pk_mul_f32 v[18:19], v[16:17], v[32:33] op_sel_hi:[1,0]
	v_cvt_pk_bf16_f32 v16, v20, v21
	v_lshl_add_u64 v[20:21], v[112:113], 0, v[142:143]
	v_cvt_pk_bf16_f32 v17, v22, v23
	v_cvt_pk_bf16_f32 v18, v18, v19
	v_cvt_pk_bf16_f32 v19, v24, v25
	global_store_dwordx4 v[20:21], v[16:19], off sc1 nt
	s_nop 1
	v_fmamk_f32 v16, v248, 0x3a800000, v230
	v_cmp_gt_f32_e32 vcc, s37, v16
	v_mul_f32_e32 v17, 0x4b800000, v16
	s_nop 0
	v_cndmask_b32_e32 v16, v16, v17, vcc
	v_rsq_f32_e32 v16, v16
	s_nop 0
	v_mul_f32_e32 v17, 0x45800000, v16
	v_cndmask_b32_e32 v16, v16, v17, vcc
	v_mul_f32_e32 v16, v157, v16
	v_pk_mul_f32 v[12:13], v[12:13], v[16:17] op_sel_hi:[1,0]
	v_pk_mul_f32 v[14:15], v[14:15], v[16:17] op_sel_hi:[1,0]
	v_pk_mul_f32 v[18:19], v[10:11], v[16:17] op_sel_hi:[1,0]
	v_pk_mul_f32 v[10:11], v[8:9], v[16:17] op_sel_hi:[1,0]
	v_cvt_pk_bf16_f32 v8, v12, v13
	v_cvt_pk_bf16_f32 v9, v14, v15
	v_lshl_add_u64 v[12:13], v[120:121], 0, v[140:141]
	v_pk_mul_f32 v[4:5], v[4:5], v[16:17] op_sel_hi:[1,0]
	v_cvt_pk_bf16_f32 v10, v10, v11
	v_cvt_pk_bf16_f32 v11, v18, v19
	global_store_dwordx4 v[12:13], v[8:11], off sc1 nt
	s_andn2_b64 vcc, exec, s[4:5]
	v_pk_mul_f32 v[6:7], v[6:7], v[16:17] op_sel_hi:[1,0]
	v_pk_mul_f32 v[8:9], v[2:3], v[16:17] op_sel_hi:[1,0]
	v_pk_mul_f32 v[2:3], v[0:1], v[16:17] op_sel_hi:[1,0]
	v_cvt_pk_bf16_f32 v0, v4, v5
	v_lshl_add_u64 v[4:5], v[112:113], 0, v[140:141]
	v_cvt_pk_bf16_f32 v1, v6, v7
	v_cvt_pk_bf16_f32 v2, v2, v3
	v_cvt_pk_bf16_f32 v3, v8, v9
	global_store_dwordx4 v[4:5], v[0:3], off sc1 nt
	s_cbranch_vccnz .LBB0_131
	s_andn2_b64 vcc, exec, s[8:9]
	s_cbranch_vccnz .LBB0_130
	s_barrier
	s_branch .LBB0_130
